# stream unit with 3 two-load units (6 loads) in flight per wave
# baseline (speedup 1.0000x reference)
.LBB0_538:
	s_or_b64 exec, exec, s[0:1]
	s_ashr_i32 s7, s20, 3
	s_ashr_i32 s4, s23, 8
	s_and_b32 s94, s20, 31
	s_lshl_b32 s94, s94, 13
	s_lshl_b32 s0, s7, 6
	s_ashr_i32 s1, s0, 31
	s_lshl_b32 s26, s4, 2
	s_and_b32 s6, s20, 7
	s_ashr_i32 s27, s26, 31
	s_lshl_b64 s[0:1], s[0:1], 2
	s_add_u32 s0, s76, s0
	s_addc_u32 s1, s77, s1
	s_lshl_b32 s23, s6, 5
	s_add_u32 s23, s0, s23
	s_addc_u32 s28, s1, 0
	s_lshl_b32 s0, s22, 14
	s_add_i32 s25, s0, 0
	s_lshl_b64 s[0:1], s[26:27], 2
	s_add_u32 s0, s23, s0
	s_addc_u32 s1, s28, s1
	s_load_dwordx2 s[98:99], s[0:1], 0x0
	s_load_dwordx2 s[100:101], s[0:1], 0x8
	global_load_dword v18, v183, s[0:1]
	v_bfe_u32 v19, v20, 4, 2
	v_and_b32_e32 v192, 63, v20
	v_lshlrev_b32_e32 v103, 3, v20
	v_lshrrev_b32_e32 v21, 2, v190
	v_lshlrev_b32_e32 v191, 2, v19
	s_waitcnt vmcnt(39)
	v_xor_b32_e32 v22, v19, v190
	v_bitop3_b32 v23, v19, v190, 4 bitop3:0x36
	v_bitop3_b32 v24, v19, v190, 8 bitop3:0x36
	v_bitop3_b32 v25, v19, v190, 12 bitop3:0x36
	v_and_b32_e32 v105, 24, v103
	v_lshrrev_b32_e32 v182, 5, v192
	v_or_b32_e32 v19, v191, v21
	v_lshl_or_b32 v122, v19, 8, v105
	v_lshlrev_b32_e32 v19, 5, v19
	s_movk_i32 s23, 0xe0
	v_and_b32_e32 v123, 0xe0, v19
	v_bitop3_b32 v124, v19, s23, v122 bitop3:0x26
	v_and_b32_e32 v102, 31, v20
	v_bfe_u32 v104, v20, 2, 3
	v_lshlrev_b32_e32 v20, 8, v190
	v_lshl_or_b32 v114, v22, 4, v20
	v_lshl_or_b32 v115, v23, 4, v20
	v_lshl_or_b32 v116, v24, 4, v20
	v_lshl_or_b32 v117, v25, 4, v20
	v_or_b32_e32 v178, 10, v182
	v_lshl_add_u32 v181, v178, 8, s25
	v_lshlrev_b32_e32 v184, 4, v178
	v_bitop3_b32 v178, v178, v104, 3 bitop3:0x6c
	v_lshl_add_u32 v205, v178, 5, v181
	v_or_b32_e32 v178, 12, v182
	v_bitop3_b32 v186, v184, v103, s19 bitop3:0x78
	v_lshl_add_u32 v206, v178, 8, s25
	v_lshlrev_b32_e32 v184, 4, v178
	v_bitop3_b32 v178, v178, v104, 5 bitop3:0x6c
	v_lshl_add_u32 v208, v178, 5, v206
	v_or_b32_e32 v178, 14, v182
	v_or_b32_e32 v131, 4, v182
	v_or_b32_e32 v134, 6, v182
	v_or_b32_e32 v137, 8, v182
	v_bitop3_b32 v207, v184, v103, s19 bitop3:0x78
	v_lshl_add_u32 v209, v178, 8, s25
	v_lshlrev_b32_e32 v184, 4, v178
	v_bitop3_b32 v178, v178, v104, 7 bitop3:0x6c
	v_lshl_add_u32 v132, v131, 8, s25
	v_lshlrev_b32_e32 v131, 4, v131
	v_lshl_add_u32 v135, v134, 8, s25
	v_lshlrev_b32_e32 v134, 4, v134
	v_lshl_add_u32 v179, v137, 8, s25
	v_lshlrev_b32_e32 v137, 4, v137
	v_lshl_add_u32 v210, v178, 5, v209
	v_or_b32_e32 v178, 18, v182
	v_bitop3_b32 v131, v131, v103, s19 bitop3:0x78
	v_bitop3_b32 v134, v134, v103, s19 bitop3:0x78
	v_bitop3_b32 v137, v137, v103, s19 bitop3:0x78
	v_lshl_add_u32 v211, v178, 8, s25
	s_movk_i32 s23, 0x60
	v_bitop3_b32 v127, v123, s23, v122 bitop3:0x36
	s_movk_i32 s23, 0x80
	v_bitop3_b32 v128, v123, s23, v122 bitop3:0x36
	s_movk_i32 s23, 0xa0
	v_bitop3_b32 v129, v123, s23, v122 bitop3:0x36
	s_movk_i32 s23, 0xc0
	v_bitop3_b32 v133, v182, v104, 4 bitop3:0x36
	v_bitop3_b32 v136, v182, v104, 6 bitop3:0x36
	v_bitop3_b32 v125, v123, 32, v122 bitop3:0x36
	v_bitop3_b32 v126, v123, 64, v122 bitop3:0x36
	v_bitop3_b32 v130, v123, s23, v122 bitop3:0x36
	s_lshl_b32 s23, s21, 7
	v_lshl_add_u32 v133, v133, 5, v132
	v_lshl_add_u32 v136, v136, 5, v135
	v_add_u32_e32 v123, s25, v123
	s_mov_b32 s22, 32
	v_add_u32_e32 v198, v132, v131
	v_add_u32_e32 v199, v133, v105
	v_add_u32_e32 v200, v135, v134
	v_add_u32_e32 v201, v136, v105
	v_add_u32_e32 v202, v179, v137
	v_add_u32_e32 v204, v181, v186
	v_add_u32_e32 v205, v205, v105
	s_waitcnt vmcnt(0)
	v_readfirstlane_b32 s26, v18
	s_ashr_i32 s27, s26, 31
	s_lshl_b64 s[26:27], s[26:27], 9
	v_lshl_or_b32 v18, v182, 2, s26
	v_mov_b32_e32 v19, s27
	v_or_b32_e32 v18, s21, v18
	v_lshlrev_b64 v[18:19], 9, v[18:19]
	v_lshl_or_b32 v18, v102, 4, v18
	v_lshl_add_u64 v[94:95], s[72:73], 0, v[18:19]
	v_add_co_u32_e32 v30, vcc, s11, v94
	v_lshl_add_u64 v[96:97], s[74:75], 0, v[18:19]
	s_nop 0
	v_addc_co_u32_e32 v31, vcc, 0, v95, vcc
	v_add_co_u32_e32 v38, vcc, s11, v96
	v_addc_co_u32_e32 v39, vcc, 0, v97, vcc
	v_add_co_u32_e32 v46, vcc, s10, v94
	s_movk_i32 s26, 0x50
	s_nop 0
	v_addc_co_u32_e32 v47, vcc, 0, v95, vcc
	v_add_co_u32_e32 v54, vcc, s10, v96
	v_add_u32_e32 v206, v206, v207
	s_nop 0
	v_addc_co_u32_e32 v55, vcc, 0, v97, vcc
	v_add_co_u32_e32 v62, vcc, s12, v94
	v_add_u32_e32 v207, v208, v105
	s_nop 0
	v_addc_co_u32_e32 v63, vcc, 0, v95, vcc
	v_add_co_u32_e32 v70, vcc, s12, v96
	v_add_u32_e32 v234, s25, v125
	s_nop 0
	v_addc_co_u32_e32 v71, vcc, 0, v97, vcc
	v_add_co_u32_e32 v78, vcc, s13, v94
	s_nop 0
	s_nop 0
	s_nop 0
	s_nop 0
	s_nop 0
	s_nop 0
	s_nop 0
	s_nop 0
	s_nop 0
	s_nop 0
	s_nop 0
	v_addc_co_u32_e32 v79, vcc, 0, v95, vcc
	v_add_co_u32_e32 v86, vcc, s13, v96
	v_add_u32_e32 v235, s25, v126
	s_nop 0
	v_addc_co_u32_e32 v87, vcc, 0, v97, vcc
	v_add_co_u32_e32 v98, vcc, s14, v94
	s_nop 0
	s_nop 0
	s_nop 0
	v_addc_co_u32_e32 v99, vcc, 0, v95, vcc
	v_add_co_u32_e32 v100, vcc, s14, v96
	v_add_u32_e32 v236, s25, v127
	s_nop 0
	v_addc_co_u32_e32 v101, vcc, 0, v97, vcc
	v_add_co_u32_e32 v98, vcc, s15, v94
	v_add_u32_e32 v237, s25, v128
	s_nop 0
	v_addc_co_u32_e32 v99, vcc, 0, v95, vcc
	v_add_co_u32_e32 v100, vcc, s15, v96
	v_add_u32_e32 v238, s25, v129
	s_nop 0
	v_addc_co_u32_e32 v101, vcc, 0, v97, vcc
	v_add_co_u32_e32 v98, vcc, s17, v94
	v_add_u32_e32 v239, s25, v130
	s_nop 0
	v_addc_co_u32_e32 v99, vcc, 0, v95, vcc
	v_add_co_u32_e32 v100, vcc, s17, v96
	v_add_u32_e32 v240, s25, v124
	s_nop 0
	v_addc_co_u32_e32 v101, vcc, 0, v97, vcc
	v_add_co_u32_e32 v94, vcc, s18, v94
	v_addc_co_u32_e32 v95, vcc, 0, v95, vcc
	v_add_co_u32_e32 v94, vcc, s18, v96
	v_or_b32_e32 v99, 2, v182
	s_nop 0
	v_addc_co_u32_e32 v95, vcc, 0, v97, vcc
	v_lshlrev_b32_e32 v96, 4, v182
	v_lshl_add_u32 v100, v99, 8, s25
	v_lshlrev_b32_e32 v99, 4, v99
	v_and_b32_e32 v94, 0xf8, v103
	v_bitop3_b32 v96, v103, v96, s19 bitop3:0x6c
	v_bitop3_b32 v99, v99, v103, s19 bitop3:0x78
	v_bitop3_b32 v103, v184, v103, s19 bitop3:0x78
	v_lshlrev_b32_e32 v184, 4, v178
	v_bitop3_b32 v178, v178, v104, 3 bitop3:0x6c
	v_lshl_add_u32 v213, v178, 5, v211
	v_or_b32_e32 v178, 20, v182
	v_bitop3_b32 v212, v184, v94, 48 bitop3:0x6c
	v_lshl_add_u32 v214, v178, 8, s25
	v_lshlrev_b32_e32 v184, 4, v178
	v_bitop3_b32 v178, v178, v104, 5 bitop3:0x6c
	v_lshl_add_u32 v216, v178, 5, v214
	v_or_b32_e32 v178, 22, v182
	v_bitop3_b32 v215, v184, v94, s26 bitop3:0x6c
	v_lshl_add_u32 v217, v178, 8, s25
	v_lshlrev_b32_e32 v184, 4, v178
	v_bitop3_b32 v178, v178, v104, 7 bitop3:0x6c
	s_movk_i32 s26, 0x70
	v_lshl_add_u32 v219, v178, 5, v217
	v_or_b32_e32 v178, 24, v182
	v_bitop3_b32 v218, v184, v94, s26 bitop3:0x6c
	v_lshl_add_u32 v220, v178, 8, s25
	v_lshlrev_b32_e32 v178, 4, v178
	s_movk_i32 s26, 0x90
	v_bitop3_b32 v221, v178, v94, s26 bitop3:0x6c
	v_or_b32_e32 v178, 26, v182
	v_lshl_add_u32 v227, v178, 8, s25
	v_lshlrev_b32_e32 v184, 4, v178
	v_bitop3_b32 v178, v178, v104, 3 bitop3:0x6c
	s_movk_i32 s26, 0xb0
	v_lshl_add_u32 v229, v178, 5, v227
	v_or_b32_e32 v178, 28, v182
	v_bitop3_b32 v228, v184, v94, s26 bitop3:0x6c
	v_lshl_add_u32 v230, v178, 8, s25
	v_lshlrev_b32_e32 v184, 4, v178
	v_bitop3_b32 v178, v178, v104, 5 bitop3:0x6c
	v_xor_b32_e32 v97, v182, v104
	s_movk_i32 s26, 0xd0
	v_lshl_add_u32 v232, v178, 5, v230
	v_or_b32_e32 v178, 30, v182
	v_lshl_add_u32 v95, v182, 8, s25
	v_lshlrev_b32_e32 v97, 5, v97
	v_bitop3_b32 v101, v182, v104, 2 bitop3:0x36
	v_bitop3_b32 v231, v184, v94, s26 bitop3:0x6c
	v_lshl_add_u32 v233, v178, 8, s25
	v_lshlrev_b32_e32 v184, 4, v178
	s_movk_i32 s26, 0xf0
	v_bitop3_b32 v104, v178, v104, 7 bitop3:0x6c
	v_add_u32_e32 v98, v95, v97
	v_lshl_add_u32 v101, v101, 5, v100
	v_add_u32_e32 v180, v179, v97
	v_add_u32_e32 v97, v220, v97
	v_bitop3_b32 v94, v184, v94, s26 bitop3:0x6c
	v_lshl_add_u32 v104, v104, 5, v233
	v_lshl_or_b32 v184, v102, 2, s23
	v_lshlrev_b32_e32 v184, 2, v184
	v_lshl_or_b32 v184, v182, 11, v184
	v_mov_b32_e32 v178, 0xf149f2ca
	v_add_u32_e32 v194, v95, v96
	v_add_u32_e32 v195, v98, v105
	v_add_u32_e32 v196, v100, v99
	v_add_u32_e32 v197, v101, v105
	v_add_u32_e32 v203, v180, v105
	v_add_u32_e32 v208, v209, v103
	v_add_u32_e32 v209, v210, v105
	v_add_u32_e32 v210, v211, v212
	v_add_u32_e32 v211, v213, v105
	v_add_u32_e32 v212, v214, v215
	v_add_u32_e32 v213, v216, v105
	v_add_u32_e32 v214, v217, v218
	v_add_u32_e32 v215, v219, v105
	v_add_u32_e32 v216, v220, v221
	v_add_u32_e32 v217, v97, v105
	v_add_u32_e32 v218, v227, v228
	v_add_u32_e32 v219, v229, v105
	v_add_u32_e32 v220, v230, v231
	v_add_u32_e32 v221, v232, v105
	v_add_u32_e32 v227, v233, v94
	v_add_u32_e32 v228, v104, v105
	s_lshl_b32 s23, s23, 2
	v_add_u32_e32 v229, s25, v114
	v_add_u32_e32 v230, s25, v115
	v_add_u32_e32 v231, s25, v116
	v_add_u32_e32 v232, s25, v117
	v_add_u32_e32 v233, v123, v122
	v_mov_b32_e32 v94, 0
	v_mov_b32_e32 v95, v193
	v_mov_b32_e32 v96, v193
	v_mov_b32_e32 v97, v193
	v_mov_b32_e32 v98, 0
	v_mov_b32_e32 v99, v193
	v_mov_b32_e32 v100, v193
	v_mov_b32_e32 v101, v193
	v_mov_b32_e32 v102, 0
	v_mov_b32_e32 v103, v193
	v_mov_b32_e32 v104, v193
	v_mov_b32_e32 v105, v193
	v_mov_b32_e32 v114, 0
	v_mov_b32_e32 v115, v193
	v_mov_b32_e32 v116, v193
	v_mov_b32_e32 v117, v193
	v_mov_b32_e32 v122, 0
	v_mov_b32_e32 v123, v193
	v_mov_b32_e32 v124, v193
	v_mov_b32_e32 v125, v193
	v_mov_b32_e32 v126, 0
	v_mov_b32_e32 v127, v193
	v_mov_b32_e32 v128, v193
	v_mov_b32_e32 v129, v193
	v_mov_b32_e32 v130, 0
	v_mov_b32_e32 v131, v193
	v_mov_b32_e32 v132, v193
	v_mov_b32_e32 v133, v193
	v_mov_b32_e32 v134, 0
	v_mov_b32_e32 v135, v193
	v_mov_b32_e32 v136, v193
	v_mov_b32_e32 v137, v193
	s_waitcnt lgkmcnt(0)
	s_lshl_b32 s95, s98, 18
	s_add_u32 s95, s95, 0x1000
	s_add_u32 s30, s95, s94
	s_add_u32 s26, s72, s30
	s_addc_u32 s27, s73, 0
	s_add_u32 s28, s74, s30
	s_addc_u32 s29, s75, 0
	s_add_u32 s94, s94, 0x2000
	s_and_b32 s94, s94, 0x3ffff
	global_load_dwordx4 v[18:21], v184, s[26:27] offset:-4096 nt
	global_load_dwordx4 v[22:25], v184, s[28:29] offset:-4096 nt
	global_load_dwordx4 v[26:29], v184, s[26:27] nt
	global_load_dwordx4 v[34:37], v184, s[28:29] nt
	s_add_u32 s30, s95, s94
	s_add_u32 s26, s72, s30
	s_addc_u32 s27, s73, 0
	s_add_u32 s28, s74, s30
	s_addc_u32 s29, s75, 0
	s_add_u32 s94, s94, 0x2000
	s_and_b32 s94, s94, 0x3ffff
	global_load_dwordx4 v[30:33], v184, s[26:27] offset:-4096 nt
	global_load_dwordx4 v[38:41], v184, s[28:29] offset:-4096 nt
.LBB0_539:
	s_add_i32 s25, s24, 1
	s_cmp_eq_u32 s24, 15
	s_cbranch_scc1 .Lsp_last_a
	s_waitcnt vmcnt(4)
	v_cvt_pk_bf16_f32 v244, v18, v19
	v_cvt_pk_bf16_f32 v245, v20, v21
	ds_write_b64 v194, v[244:245]
	v_cvt_pk_bf16_f32 v180, v22, v23
	v_cvt_pk_bf16_f32 v181, v24, v25
	ds_write_b64 v195, v[180:181] offset:8192
	global_load_dwordx4 v[42:45], v184, s[26:27] nt
	global_load_dwordx4 v[50:53], v184, s[28:29] nt
	s_waitcnt vmcnt(4)
	v_cvt_pk_bf16_f32 v244, v26, v27
	v_cvt_pk_bf16_f32 v245, v28, v29
	ds_write_b64 v196, v[244:245]
	v_cvt_pk_bf16_f32 v180, v34, v35
	v_cvt_pk_bf16_f32 v181, v36, v37
	ds_write_b64 v197, v[180:181] offset:8192
	s_add_u32 s30, s95, s94
	s_add_u32 s26, s72, s30
	s_addc_u32 s27, s73, 0
	s_add_u32 s28, s74, s30
	s_addc_u32 s29, s75, 0
	s_add_u32 s94, s94, 0x2000
	s_and_b32 s94, s94, 0x3ffff
	global_load_dwordx4 v[46:49], v184, s[26:27] offset:-4096 nt
	global_load_dwordx4 v[54:57], v184, s[28:29] offset:-4096 nt
	s_waitcnt vmcnt(4)
	v_cvt_pk_bf16_f32 v244, v30, v31
	v_cvt_pk_bf16_f32 v245, v32, v33
	ds_write_b64 v198, v[244:245]
	v_cvt_pk_bf16_f32 v180, v38, v39
	v_cvt_pk_bf16_f32 v181, v40, v41
	ds_write_b64 v199, v[180:181] offset:8192
	global_load_dwordx4 v[58:61], v184, s[26:27] nt
	global_load_dwordx4 v[66:69], v184, s[28:29] nt
	s_waitcnt vmcnt(4)
	v_cvt_pk_bf16_f32 v244, v42, v43
	v_cvt_pk_bf16_f32 v245, v44, v45
	ds_write_b64 v200, v[244:245]
	v_cvt_pk_bf16_f32 v180, v50, v51
	v_cvt_pk_bf16_f32 v181, v52, v53
	ds_write_b64 v201, v[180:181] offset:8192
	s_add_u32 s30, s95, s94
	s_add_u32 s26, s72, s30
	s_addc_u32 s27, s73, 0
	s_add_u32 s28, s74, s30
	s_addc_u32 s29, s75, 0
	s_add_u32 s94, s94, 0x2000
	s_and_b32 s94, s94, 0x3ffff
	global_load_dwordx4 v[62:65], v184, s[26:27] offset:-4096 nt
	global_load_dwordx4 v[70:73], v184, s[28:29] offset:-4096 nt
	s_waitcnt vmcnt(4)
	v_cvt_pk_bf16_f32 v244, v46, v47
	v_cvt_pk_bf16_f32 v245, v48, v49
	ds_write_b64 v202, v[244:245]
	v_cvt_pk_bf16_f32 v180, v54, v55
	v_cvt_pk_bf16_f32 v181, v56, v57
	ds_write_b64 v203, v[180:181] offset:8192
	global_load_dwordx4 v[74:77], v184, s[26:27] nt
	global_load_dwordx4 v[82:85], v184, s[28:29] nt
	s_waitcnt vmcnt(4)
	v_cvt_pk_bf16_f32 v244, v58, v59
	v_cvt_pk_bf16_f32 v245, v60, v61
	ds_write_b64 v204, v[244:245]
	v_cvt_pk_bf16_f32 v180, v66, v67
	v_cvt_pk_bf16_f32 v181, v68, v69
	ds_write_b64 v205, v[180:181] offset:8192
	s_add_u32 s30, s95, s94
	s_add_u32 s26, s72, s30
	s_addc_u32 s27, s73, 0
	s_add_u32 s28, s74, s30
	s_addc_u32 s29, s75, 0
	s_add_u32 s94, s94, 0x2000
	s_and_b32 s94, s94, 0x3ffff
	global_load_dwordx4 v[78:81], v184, s[26:27] offset:-4096 nt
	global_load_dwordx4 v[86:89], v184, s[28:29] offset:-4096 nt
	s_waitcnt vmcnt(4)
	v_cvt_pk_bf16_f32 v244, v62, v63
	v_cvt_pk_bf16_f32 v245, v64, v65
	ds_write_b64 v206, v[244:245]
	v_cvt_pk_bf16_f32 v180, v70, v71
	v_cvt_pk_bf16_f32 v181, v72, v73
	ds_write_b64 v207, v[180:181] offset:8192
	global_load_dwordx4 v[90:93], v184, s[26:27] nt
	global_load_dwordx4 v[110:113], v184, s[28:29] nt
	s_waitcnt vmcnt(4)
	v_cvt_pk_bf16_f32 v244, v74, v75
	v_cvt_pk_bf16_f32 v245, v76, v77
	ds_write_b64 v208, v[244:245]
	v_cvt_pk_bf16_f32 v180, v82, v83
	v_cvt_pk_bf16_f32 v181, v84, v85
	ds_write_b64 v209, v[180:181] offset:8192
	s_add_u32 s30, s95, s94
	s_add_u32 s26, s72, s30
	s_addc_u32 s27, s73, 0
	s_add_u32 s28, s74, s30
	s_addc_u32 s29, s75, 0
	s_add_u32 s94, s94, 0x2000
	s_and_b32 s94, s94, 0x3ffff
	global_load_dwordx4 v[106:109], v184, s[26:27] offset:-4096 nt
	global_load_dwordx4 v[118:121], v184, s[28:29] offset:-4096 nt
	s_waitcnt vmcnt(4)
	v_cvt_pk_bf16_f32 v244, v78, v79
	v_cvt_pk_bf16_f32 v245, v80, v81
	ds_write_b64 v194, v[244:245] offset:4096
	v_cvt_pk_bf16_f32 v180, v86, v87
	v_cvt_pk_bf16_f32 v181, v88, v89
	ds_write_b64 v195, v[180:181] offset:12288
	global_load_dwordx4 v[138:141], v184, s[26:27] nt
	global_load_dwordx4 v[142:145], v184, s[28:29] nt
	s_waitcnt vmcnt(4)
	v_cvt_pk_bf16_f32 v244, v90, v91
	v_cvt_pk_bf16_f32 v245, v92, v93
	ds_write_b64 v210, v[244:245]
	v_cvt_pk_bf16_f32 v180, v110, v111
	v_cvt_pk_bf16_f32 v181, v112, v113
	ds_write_b64 v211, v[180:181] offset:8192
	s_add_u32 s30, s95, s94
	s_add_u32 s26, s72, s30
	s_addc_u32 s27, s73, 0
	s_add_u32 s28, s74, s30
	s_addc_u32 s29, s75, 0
	s_add_u32 s94, s94, 0x2000
	s_and_b32 s94, s94, 0x3ffff
	global_load_dwordx4 v[146:149], v184, s[26:27] offset:-4096 nt
	global_load_dwordx4 v[150:153], v184, s[28:29] offset:-4096 nt
	s_waitcnt vmcnt(4)
	v_cvt_pk_bf16_f32 v244, v106, v107
	v_cvt_pk_bf16_f32 v245, v108, v109
	ds_write_b64 v212, v[244:245]
	v_cvt_pk_bf16_f32 v180, v118, v119
	v_cvt_pk_bf16_f32 v181, v120, v121
	ds_write_b64 v213, v[180:181] offset:8192
	global_load_dwordx4 v[154:157], v184, s[26:27] nt
	global_load_dwordx4 v[158:161], v184, s[28:29] nt
	s_waitcnt vmcnt(4)
	v_cvt_pk_bf16_f32 v244, v138, v139
	v_cvt_pk_bf16_f32 v245, v140, v141
	ds_write_b64 v214, v[244:245]
	v_cvt_pk_bf16_f32 v180, v142, v143
	v_cvt_pk_bf16_f32 v181, v144, v145
	ds_write_b64 v215, v[180:181] offset:8192
	s_add_u32 s30, s95, s94
	s_add_u32 s26, s72, s30
	s_addc_u32 s27, s73, 0
	s_add_u32 s28, s74, s30
	s_addc_u32 s29, s75, 0
	s_add_u32 s94, s94, 0x2000
	s_and_b32 s94, s94, 0x3ffff
	global_load_dwordx4 v[162:165], v184, s[26:27] offset:-4096 nt
	global_load_dwordx4 v[166:169], v184, s[28:29] offset:-4096 nt
	s_waitcnt vmcnt(4)
	v_cvt_pk_bf16_f32 v244, v146, v147
	v_cvt_pk_bf16_f32 v245, v148, v149
	ds_write_b64 v216, v[244:245]
	v_cvt_pk_bf16_f32 v180, v150, v151
	v_cvt_pk_bf16_f32 v181, v152, v153
	ds_write_b64 v217, v[180:181] offset:8192
	global_load_dwordx4 v[170:173], v184, s[26:27] nt
	global_load_dwordx4 v[174:177], v184, s[28:29] nt
	s_lshr_b32 s30, s25, 2
	s_cmp_lt_u32 s30, 2
	s_cselect_b32 s95, s98, s100
	s_cselect_b32 s97, s99, s101
	s_bitcmp1_b32 s30, 0
	s_cselect_b32 s95, s97, s95
	s_lshl_b32 s95, s95, 18
	s_add_u32 s95, s95, 0x1000
	s_waitcnt vmcnt(4)
	v_cvt_pk_bf16_f32 v244, v154, v155
	v_cvt_pk_bf16_f32 v245, v156, v157
	ds_write_b64 v218, v[244:245]
	v_cvt_pk_bf16_f32 v180, v158, v159
	v_cvt_pk_bf16_f32 v181, v160, v161
	ds_write_b64 v219, v[180:181] offset:8192
	s_add_u32 s30, s95, s94
	s_add_u32 s26, s72, s30
	s_addc_u32 s27, s73, 0
	s_add_u32 s28, s74, s30
	s_addc_u32 s29, s75, 0
	s_add_u32 s94, s94, 0x2000
	s_and_b32 s94, s94, 0x3ffff
	global_load_dwordx4 v[18:21], v184, s[26:27] offset:-4096 nt
	global_load_dwordx4 v[22:25], v184, s[28:29] offset:-4096 nt
	s_waitcnt vmcnt(4)
	v_cvt_pk_bf16_f32 v244, v162, v163
	v_cvt_pk_bf16_f32 v245, v164, v165
	ds_write_b64 v220, v[244:245]
	v_cvt_pk_bf16_f32 v180, v166, v167
	v_cvt_pk_bf16_f32 v181, v168, v169
	ds_write_b64 v221, v[180:181] offset:8192
	global_load_dwordx4 v[26:29], v184, s[26:27] nt
	global_load_dwordx4 v[34:37], v184, s[28:29] nt
	s_waitcnt vmcnt(4)
	v_cvt_pk_bf16_f32 v244, v170, v171
	v_cvt_pk_bf16_f32 v245, v172, v173
	ds_write_b64 v227, v[244:245]
	v_cvt_pk_bf16_f32 v180, v174, v175
	v_cvt_pk_bf16_f32 v181, v176, v177
	ds_write_b64 v228, v[180:181] offset:8192
	s_add_u32 s30, s95, s94
	s_add_u32 s26, s72, s30
	s_addc_u32 s27, s73, 0
	s_add_u32 s28, s74, s30
	s_addc_u32 s29, s75, 0
	s_add_u32 s94, s94, 0x2000
	s_and_b32 s94, s94, 0x3ffff
	global_load_dwordx4 v[30:33], v184, s[26:27] offset:-4096 nt
	global_load_dwordx4 v[38:41], v184, s[28:29] offset:-4096 nt
	s_branch .LBB0_543
.Lsp_last_a:
	s_waitcnt vmcnt(4)
	v_cvt_pk_bf16_f32 v244, v18, v19
	v_cvt_pk_bf16_f32 v245, v20, v21
	ds_write_b64 v194, v[244:245]
	v_cvt_pk_bf16_f32 v180, v22, v23
	v_cvt_pk_bf16_f32 v181, v24, v25
	ds_write_b64 v195, v[180:181] offset:8192
	global_load_dwordx4 v[42:45], v184, s[26:27] nt
	global_load_dwordx4 v[50:53], v184, s[28:29] nt
	s_waitcnt vmcnt(4)
	v_cvt_pk_bf16_f32 v244, v26, v27
	v_cvt_pk_bf16_f32 v245, v28, v29
	ds_write_b64 v196, v[244:245]
	v_cvt_pk_bf16_f32 v180, v34, v35
	v_cvt_pk_bf16_f32 v181, v36, v37
	ds_write_b64 v197, v[180:181] offset:8192
	s_add_u32 s30, s95, s94
	s_add_u32 s26, s72, s30
	s_addc_u32 s27, s73, 0
	s_add_u32 s28, s74, s30
	s_addc_u32 s29, s75, 0
	s_add_u32 s94, s94, 0x2000
	s_and_b32 s94, s94, 0x3ffff
	global_load_dwordx4 v[46:49], v184, s[26:27] offset:-4096 nt
	global_load_dwordx4 v[54:57], v184, s[28:29] offset:-4096 nt
	s_waitcnt vmcnt(4)
	v_cvt_pk_bf16_f32 v244, v30, v31
	v_cvt_pk_bf16_f32 v245, v32, v33
	ds_write_b64 v198, v[244:245]
	v_cvt_pk_bf16_f32 v180, v38, v39
	v_cvt_pk_bf16_f32 v181, v40, v41
	ds_write_b64 v199, v[180:181] offset:8192
	global_load_dwordx4 v[58:61], v184, s[26:27] nt
	global_load_dwordx4 v[66:69], v184, s[28:29] nt
	s_waitcnt vmcnt(4)
	v_cvt_pk_bf16_f32 v244, v42, v43
	v_cvt_pk_bf16_f32 v245, v44, v45
	ds_write_b64 v200, v[244:245]
	v_cvt_pk_bf16_f32 v180, v50, v51
	v_cvt_pk_bf16_f32 v181, v52, v53
	ds_write_b64 v201, v[180:181] offset:8192
	s_add_u32 s30, s95, s94
	s_add_u32 s26, s72, s30
	s_addc_u32 s27, s73, 0
	s_add_u32 s28, s74, s30
	s_addc_u32 s29, s75, 0
	s_add_u32 s94, s94, 0x2000
	s_and_b32 s94, s94, 0x3ffff
	global_load_dwordx4 v[62:65], v184, s[26:27] offset:-4096 nt
	global_load_dwordx4 v[70:73], v184, s[28:29] offset:-4096 nt
	s_waitcnt vmcnt(4)
	v_cvt_pk_bf16_f32 v244, v46, v47
	v_cvt_pk_bf16_f32 v245, v48, v49
	ds_write_b64 v202, v[244:245]
	v_cvt_pk_bf16_f32 v180, v54, v55
	v_cvt_pk_bf16_f32 v181, v56, v57
	ds_write_b64 v203, v[180:181] offset:8192
	global_load_dwordx4 v[74:77], v184, s[26:27] nt
	global_load_dwordx4 v[82:85], v184, s[28:29] nt
	s_waitcnt vmcnt(4)
	v_cvt_pk_bf16_f32 v244, v58, v59
	v_cvt_pk_bf16_f32 v245, v60, v61
	ds_write_b64 v204, v[244:245]
	v_cvt_pk_bf16_f32 v180, v66, v67
	v_cvt_pk_bf16_f32 v181, v68, v69
	ds_write_b64 v205, v[180:181] offset:8192
	s_add_u32 s30, s95, s94
	s_add_u32 s26, s72, s30
	s_addc_u32 s27, s73, 0
	s_add_u32 s28, s74, s30
	s_addc_u32 s29, s75, 0
	s_add_u32 s94, s94, 0x2000
	s_and_b32 s94, s94, 0x3ffff
	global_load_dwordx4 v[78:81], v184, s[26:27] offset:-4096 nt
	global_load_dwordx4 v[86:89], v184, s[28:29] offset:-4096 nt
	s_waitcnt vmcnt(4)
	v_cvt_pk_bf16_f32 v244, v62, v63
	v_cvt_pk_bf16_f32 v245, v64, v65
	ds_write_b64 v206, v[244:245]
	v_cvt_pk_bf16_f32 v180, v70, v71
	v_cvt_pk_bf16_f32 v181, v72, v73
	ds_write_b64 v207, v[180:181] offset:8192
	global_load_dwordx4 v[90:93], v184, s[26:27] nt
	global_load_dwordx4 v[110:113], v184, s[28:29] nt
	s_waitcnt vmcnt(4)
	v_cvt_pk_bf16_f32 v244, v74, v75
	v_cvt_pk_bf16_f32 v245, v76, v77
	ds_write_b64 v208, v[244:245]
	v_cvt_pk_bf16_f32 v180, v82, v83
	v_cvt_pk_bf16_f32 v181, v84, v85
	ds_write_b64 v209, v[180:181] offset:8192
	s_add_u32 s30, s95, s94
	s_add_u32 s26, s72, s30
	s_addc_u32 s27, s73, 0
	s_add_u32 s28, s74, s30
	s_addc_u32 s29, s75, 0
	s_add_u32 s94, s94, 0x2000
	s_and_b32 s94, s94, 0x3ffff
	global_load_dwordx4 v[106:109], v184, s[26:27] offset:-4096 nt
	global_load_dwordx4 v[118:121], v184, s[28:29] offset:-4096 nt
	s_waitcnt vmcnt(4)
	v_cvt_pk_bf16_f32 v244, v78, v79
	v_cvt_pk_bf16_f32 v245, v80, v81
	ds_write_b64 v194, v[244:245] offset:4096
	v_cvt_pk_bf16_f32 v180, v86, v87
	v_cvt_pk_bf16_f32 v181, v88, v89
	ds_write_b64 v195, v[180:181] offset:12288
	global_load_dwordx4 v[138:141], v184, s[26:27] nt
	global_load_dwordx4 v[142:145], v184, s[28:29] nt
	s_waitcnt vmcnt(4)
	v_cvt_pk_bf16_f32 v244, v90, v91
	v_cvt_pk_bf16_f32 v245, v92, v93
	ds_write_b64 v210, v[244:245]
	v_cvt_pk_bf16_f32 v180, v110, v111
	v_cvt_pk_bf16_f32 v181, v112, v113
	ds_write_b64 v211, v[180:181] offset:8192
	s_add_u32 s30, s95, s94
	s_add_u32 s26, s72, s30
	s_addc_u32 s27, s73, 0
	s_add_u32 s28, s74, s30
	s_addc_u32 s29, s75, 0
	s_add_u32 s94, s94, 0x2000
	s_and_b32 s94, s94, 0x3ffff
	global_load_dwordx4 v[146:149], v184, s[26:27] offset:-4096 nt
	global_load_dwordx4 v[150:153], v184, s[28:29] offset:-4096 nt
	s_waitcnt vmcnt(4)
	v_cvt_pk_bf16_f32 v244, v106, v107
	v_cvt_pk_bf16_f32 v245, v108, v109
	ds_write_b64 v212, v[244:245]
	v_cvt_pk_bf16_f32 v180, v118, v119
	v_cvt_pk_bf16_f32 v181, v120, v121
	ds_write_b64 v213, v[180:181] offset:8192
	global_load_dwordx4 v[154:157], v184, s[26:27] nt
	global_load_dwordx4 v[158:161], v184, s[28:29] nt
	s_waitcnt vmcnt(4)
	v_cvt_pk_bf16_f32 v244, v138, v139
	v_cvt_pk_bf16_f32 v245, v140, v141
	ds_write_b64 v214, v[244:245]
	v_cvt_pk_bf16_f32 v180, v142, v143
	v_cvt_pk_bf16_f32 v181, v144, v145
	ds_write_b64 v215, v[180:181] offset:8192
	s_add_u32 s30, s95, s94
	s_add_u32 s26, s72, s30
	s_addc_u32 s27, s73, 0
	s_add_u32 s28, s74, s30
	s_addc_u32 s29, s75, 0
	s_add_u32 s94, s94, 0x2000
	s_and_b32 s94, s94, 0x3ffff
	global_load_dwordx4 v[162:165], v184, s[26:27] offset:-4096 nt
	global_load_dwordx4 v[166:169], v184, s[28:29] offset:-4096 nt
	s_waitcnt vmcnt(4)
	v_cvt_pk_bf16_f32 v244, v146, v147
	v_cvt_pk_bf16_f32 v245, v148, v149
	ds_write_b64 v216, v[244:245]
	v_cvt_pk_bf16_f32 v180, v150, v151
	v_cvt_pk_bf16_f32 v181, v152, v153
	ds_write_b64 v217, v[180:181] offset:8192
	global_load_dwordx4 v[170:173], v184, s[26:27] nt
	global_load_dwordx4 v[174:177], v184, s[28:29] nt
	s_waitcnt vmcnt(4)
	v_cvt_pk_bf16_f32 v244, v154, v155
	v_cvt_pk_bf16_f32 v245, v156, v157
	ds_write_b64 v218, v[244:245]
	v_cvt_pk_bf16_f32 v180, v158, v159
	v_cvt_pk_bf16_f32 v181, v160, v161
	ds_write_b64 v219, v[180:181] offset:8192
	s_waitcnt vmcnt(2)
	v_cvt_pk_bf16_f32 v244, v162, v163
	v_cvt_pk_bf16_f32 v245, v164, v165
	ds_write_b64 v220, v[244:245]
	v_cvt_pk_bf16_f32 v180, v166, v167
	v_cvt_pk_bf16_f32 v181, v168, v169
	ds_write_b64 v221, v[180:181] offset:8192
	s_waitcnt vmcnt(0)
	v_cvt_pk_bf16_f32 v244, v170, v171
	v_cvt_pk_bf16_f32 v245, v172, v173
	ds_write_b64 v227, v[244:245]
	v_cvt_pk_bf16_f32 v180, v174, v175
	v_cvt_pk_bf16_f32 v181, v176, v177
	ds_write_b64 v228, v[180:181] offset:8192
	s_branch .LBB0_543

.LBB0_595:
	s_or_b64 exec, exec, s[0:1]
	s_ashr_i32 s7, s20, 3
	s_ashr_i32 s4, s23, 8
	s_and_b32 s94, s20, 31
	s_lshl_b32 s94, s94, 13
	s_lshl_b32 s0, s7, 6
	s_ashr_i32 s1, s0, 31
	s_lshl_b32 s26, s4, 2
	s_and_b32 s6, s20, 7
	s_ashr_i32 s27, s26, 31
	s_lshl_b64 s[0:1], s[0:1], 2
	s_add_u32 s0, s76, s0
	s_addc_u32 s1, s77, s1
	s_lshl_b32 s23, s6, 5
	s_add_u32 s23, s0, s23
	s_addc_u32 s28, s1, 0
	s_lshl_b32 s0, s22, 14
	s_add_i32 s25, s0, 0
	s_lshl_b64 s[0:1], s[26:27], 2
	s_add_u32 s0, s23, s0
	s_addc_u32 s1, s28, s1
	s_load_dwordx2 s[98:99], s[0:1], 0x0
	s_load_dwordx2 s[100:101], s[0:1], 0x8
	global_load_dword v18, v183, s[0:1]
	v_bfe_u32 v19, v20, 4, 2
	v_and_b32_e32 v188, 63, v20
	v_lshlrev_b32_e32 v103, 3, v20
	v_lshrrev_b32_e32 v21, 2, v185
	v_lshlrev_b32_e32 v187, 2, v19
	s_waitcnt vmcnt(39)
	v_xor_b32_e32 v22, v19, v185
	v_bitop3_b32 v23, v19, v185, 4 bitop3:0x36
	v_bitop3_b32 v24, v19, v185, 8 bitop3:0x36
	v_bitop3_b32 v25, v19, v185, 12 bitop3:0x36
	v_and_b32_e32 v105, 24, v103
	v_lshrrev_b32_e32 v182, 5, v188
	v_or_b32_e32 v19, v187, v21
	v_lshl_or_b32 v122, v19, 8, v105
	v_lshlrev_b32_e32 v19, 5, v19
	s_movk_i32 s23, 0xe0
	v_and_b32_e32 v123, 0xe0, v19
	v_bitop3_b32 v124, v19, s23, v122 bitop3:0x26
	v_and_b32_e32 v102, 31, v20
	v_bfe_u32 v104, v20, 2, 3
	v_lshlrev_b32_e32 v20, 8, v185
	v_lshl_or_b32 v114, v22, 4, v20
	v_lshl_or_b32 v115, v23, 4, v20
	v_lshl_or_b32 v116, v24, 4, v20
	v_lshl_or_b32 v117, v25, 4, v20
	v_or_b32_e32 v178, 10, v182
	v_lshl_add_u32 v181, v178, 8, s25
	v_lshlrev_b32_e32 v184, 4, v178
	v_bitop3_b32 v178, v178, v104, 3 bitop3:0x6c
	v_lshl_add_u32 v202, v178, 5, v181
	v_or_b32_e32 v178, 12, v182
	v_bitop3_b32 v186, v184, v103, s19 bitop3:0x78
	v_lshl_add_u32 v203, v178, 8, s25
	v_lshlrev_b32_e32 v184, 4, v178
	v_bitop3_b32 v178, v178, v104, 5 bitop3:0x6c
	v_lshl_add_u32 v205, v178, 5, v203
	v_or_b32_e32 v178, 14, v182
	v_or_b32_e32 v131, 4, v182
	v_or_b32_e32 v134, 6, v182
	v_or_b32_e32 v137, 8, v182
	v_bitop3_b32 v204, v184, v103, s19 bitop3:0x78
	v_lshl_add_u32 v206, v178, 8, s25
	v_lshlrev_b32_e32 v184, 4, v178
	v_bitop3_b32 v178, v178, v104, 7 bitop3:0x6c
	v_lshl_add_u32 v132, v131, 8, s25
	v_lshlrev_b32_e32 v131, 4, v131
	v_lshl_add_u32 v135, v134, 8, s25
	v_lshlrev_b32_e32 v134, 4, v134
	v_lshl_add_u32 v179, v137, 8, s25
	v_lshlrev_b32_e32 v137, 4, v137
	v_lshl_add_u32 v207, v178, 5, v206
	v_or_b32_e32 v178, 18, v182
	v_bitop3_b32 v131, v131, v103, s19 bitop3:0x78
	v_bitop3_b32 v134, v134, v103, s19 bitop3:0x78
	v_bitop3_b32 v137, v137, v103, s19 bitop3:0x78
	v_lshl_add_u32 v208, v178, 8, s25
	s_movk_i32 s23, 0x60
	v_bitop3_b32 v127, v123, s23, v122 bitop3:0x36
	s_movk_i32 s23, 0x80
	v_bitop3_b32 v128, v123, s23, v122 bitop3:0x36
	s_movk_i32 s23, 0xa0
	v_bitop3_b32 v129, v123, s23, v122 bitop3:0x36
	s_movk_i32 s23, 0xc0
	v_bitop3_b32 v133, v182, v104, 4 bitop3:0x36
	v_bitop3_b32 v136, v182, v104, 6 bitop3:0x36
	v_bitop3_b32 v125, v123, 32, v122 bitop3:0x36
	v_bitop3_b32 v126, v123, 64, v122 bitop3:0x36
	v_bitop3_b32 v130, v123, s23, v122 bitop3:0x36
	s_lshl_b32 s23, s21, 7
	v_lshl_add_u32 v133, v133, 5, v132
	v_lshl_add_u32 v136, v136, 5, v135
	v_add_u32_e32 v123, s25, v123
	s_mov_b32 s22, 32
	v_add_u32_e32 v194, v132, v131
	v_add_u32_e32 v195, v133, v105
	v_add_u32_e32 v197, v135, v134
	v_add_u32_e32 v198, v136, v105
	v_add_u32_e32 v199, v179, v137
	v_add_u32_e32 v201, v181, v186
	v_add_u32_e32 v202, v202, v105
	s_waitcnt vmcnt(0)
	v_readfirstlane_b32 s26, v18
	s_ashr_i32 s27, s26, 31
	s_lshl_b64 s[26:27], s[26:27], 9
	v_lshl_or_b32 v18, v182, 2, s26
	v_mov_b32_e32 v19, s27
	v_or_b32_e32 v18, s21, v18
	v_lshlrev_b64 v[18:19], 9, v[18:19]
	v_lshl_or_b32 v18, v102, 4, v18
	v_lshl_add_u64 v[94:95], s[72:73], 0, v[18:19]
	v_add_co_u32_e32 v30, vcc, s11, v94
	v_lshl_add_u64 v[96:97], s[74:75], 0, v[18:19]
	s_nop 0
	v_addc_co_u32_e32 v31, vcc, 0, v95, vcc
	v_add_co_u32_e32 v38, vcc, s11, v96
	v_addc_co_u32_e32 v39, vcc, 0, v97, vcc
	v_add_co_u32_e32 v46, vcc, s10, v94
	s_movk_i32 s26, 0x50
	s_nop 0
	v_addc_co_u32_e32 v47, vcc, 0, v95, vcc
	v_add_co_u32_e32 v54, vcc, s10, v96
	v_add_u32_e32 v203, v203, v204
	s_nop 0
	v_addc_co_u32_e32 v55, vcc, 0, v97, vcc
	v_add_co_u32_e32 v62, vcc, s12, v94
	v_add_u32_e32 v204, v205, v105
	s_nop 0
	v_addc_co_u32_e32 v63, vcc, 0, v95, vcc
	v_add_co_u32_e32 v70, vcc, s12, v96
	v_add_u32_e32 v231, s25, v125
	s_nop 0
	v_addc_co_u32_e32 v71, vcc, 0, v97, vcc
	v_add_co_u32_e32 v78, vcc, s13, v94
	s_nop 0
	s_nop 0
	s_nop 0
	s_nop 0
	s_nop 0
	s_nop 0
	s_nop 0
	s_nop 0
	s_nop 0
	s_nop 0
	s_nop 0
	v_addc_co_u32_e32 v79, vcc, 0, v95, vcc
	v_add_co_u32_e32 v86, vcc, s13, v96
	v_add_u32_e32 v232, s25, v126
	s_nop 0
	v_addc_co_u32_e32 v87, vcc, 0, v97, vcc
	v_add_co_u32_e32 v98, vcc, s14, v94
	s_nop 0
	s_nop 0
	s_nop 0
	v_addc_co_u32_e32 v99, vcc, 0, v95, vcc
	v_add_co_u32_e32 v100, vcc, s14, v96
	v_add_u32_e32 v233, s25, v127
	s_nop 0
	v_addc_co_u32_e32 v101, vcc, 0, v97, vcc
	v_add_co_u32_e32 v98, vcc, s15, v94
	v_add_u32_e32 v234, s25, v128
	s_nop 0
	v_addc_co_u32_e32 v99, vcc, 0, v95, vcc
	v_add_co_u32_e32 v100, vcc, s15, v96
	v_add_u32_e32 v235, s25, v129
	s_nop 0
	v_addc_co_u32_e32 v101, vcc, 0, v97, vcc
	v_add_co_u32_e32 v98, vcc, s17, v94
	v_add_u32_e32 v236, s25, v130
	s_nop 0
	v_addc_co_u32_e32 v99, vcc, 0, v95, vcc
	v_add_co_u32_e32 v100, vcc, s17, v96
	v_add_u32_e32 v237, s25, v124
	s_nop 0
	v_addc_co_u32_e32 v101, vcc, 0, v97, vcc
	v_add_co_u32_e32 v94, vcc, s18, v94
	v_addc_co_u32_e32 v95, vcc, 0, v95, vcc
	v_add_co_u32_e32 v94, vcc, s18, v96
	v_or_b32_e32 v99, 2, v182
	s_nop 0
	v_addc_co_u32_e32 v95, vcc, 0, v97, vcc
	v_lshlrev_b32_e32 v96, 4, v182
	v_lshl_add_u32 v100, v99, 8, s25
	v_lshlrev_b32_e32 v99, 4, v99
	v_and_b32_e32 v94, 0xf8, v103
	v_bitop3_b32 v96, v103, v96, s19 bitop3:0x6c
	v_bitop3_b32 v99, v99, v103, s19 bitop3:0x78
	v_bitop3_b32 v103, v184, v103, s19 bitop3:0x78
	v_lshlrev_b32_e32 v184, 4, v178
	v_bitop3_b32 v178, v178, v104, 3 bitop3:0x6c
	v_lshl_add_u32 v210, v178, 5, v208
	v_or_b32_e32 v178, 20, v182
	v_bitop3_b32 v209, v184, v94, 48 bitop3:0x6c
	v_lshl_add_u32 v211, v178, 8, s25
	v_lshlrev_b32_e32 v184, 4, v178
	v_bitop3_b32 v178, v178, v104, 5 bitop3:0x6c
	v_lshl_add_u32 v213, v178, 5, v211
	v_or_b32_e32 v178, 22, v182
	v_bitop3_b32 v212, v184, v94, s26 bitop3:0x6c
	v_lshl_add_u32 v214, v178, 8, s25
	v_lshlrev_b32_e32 v184, 4, v178
	v_bitop3_b32 v178, v178, v104, 7 bitop3:0x6c
	s_movk_i32 s26, 0x70
	v_lshl_add_u32 v216, v178, 5, v214
	v_or_b32_e32 v178, 24, v182
	v_bitop3_b32 v215, v184, v94, s26 bitop3:0x6c
	v_lshl_add_u32 v217, v178, 8, s25
	v_lshlrev_b32_e32 v178, 4, v178
	s_movk_i32 s26, 0x90
	v_bitop3_b32 v218, v178, v94, s26 bitop3:0x6c
	v_or_b32_e32 v178, 26, v182
	v_lshl_add_u32 v219, v178, 8, s25
	v_lshlrev_b32_e32 v184, 4, v178
	v_bitop3_b32 v178, v178, v104, 3 bitop3:0x6c
	s_movk_i32 s26, 0xb0
	v_lshl_add_u32 v221, v178, 5, v219
	v_or_b32_e32 v178, 28, v182
	v_bitop3_b32 v220, v184, v94, s26 bitop3:0x6c
	v_lshl_add_u32 v227, v178, 8, s25
	v_lshlrev_b32_e32 v184, 4, v178
	v_bitop3_b32 v178, v178, v104, 5 bitop3:0x6c
	v_xor_b32_e32 v97, v182, v104
	s_movk_i32 s26, 0xd0
	v_lshl_add_u32 v229, v178, 5, v227
	v_or_b32_e32 v178, 30, v182
	v_lshl_add_u32 v95, v182, 8, s25
	v_lshlrev_b32_e32 v97, 5, v97
	v_bitop3_b32 v101, v182, v104, 2 bitop3:0x36
	v_bitop3_b32 v228, v184, v94, s26 bitop3:0x6c
	v_lshl_add_u32 v230, v178, 8, s25
	v_lshlrev_b32_e32 v184, 4, v178
	s_movk_i32 s26, 0xf0
	v_bitop3_b32 v104, v178, v104, 7 bitop3:0x6c
	v_add_u32_e32 v98, v95, v97
	v_lshl_add_u32 v101, v101, 5, v100
	v_add_u32_e32 v180, v179, v97
	v_add_u32_e32 v97, v217, v97
	v_bitop3_b32 v94, v184, v94, s26 bitop3:0x6c
	v_lshl_add_u32 v104, v104, 5, v230
	v_lshl_or_b32 v184, v102, 2, s23
	v_lshlrev_b32_e32 v184, 2, v184
	v_lshl_or_b32 v184, v182, 11, v184
	v_mov_b32_e32 v178, 0xf149f2ca
	v_add_u32_e32 v190, v95, v96
	v_add_u32_e32 v191, v98, v105
	v_add_u32_e32 v192, v100, v99
	v_add_u32_e32 v193, v101, v105
	v_add_u32_e32 v200, v180, v105
	v_add_u32_e32 v205, v206, v103
	v_add_u32_e32 v206, v207, v105
	v_add_u32_e32 v207, v208, v209
	v_add_u32_e32 v208, v210, v105
	v_add_u32_e32 v209, v211, v212
	v_add_u32_e32 v210, v213, v105
	v_add_u32_e32 v211, v214, v215
	v_add_u32_e32 v212, v216, v105
	v_add_u32_e32 v213, v217, v218
	v_add_u32_e32 v214, v97, v105
	v_add_u32_e32 v215, v219, v220
	v_add_u32_e32 v216, v221, v105
	v_add_u32_e32 v217, v227, v228
	v_add_u32_e32 v218, v229, v105
	v_add_u32_e32 v219, v230, v94
	v_add_u32_e32 v220, v104, v105
	s_lshl_b32 s23, s23, 2
	v_add_u32_e32 v221, s25, v114
	v_add_u32_e32 v227, s25, v115
	v_add_u32_e32 v228, s25, v116
	v_add_u32_e32 v229, s25, v117
	v_add_u32_e32 v230, v123, v122
	v_mov_b32_e32 v94, 0
	v_mov_b32_e32 v95, v189
	v_mov_b32_e32 v96, v189
	v_mov_b32_e32 v97, v189
	v_mov_b32_e32 v98, 0
	v_mov_b32_e32 v99, v189
	v_mov_b32_e32 v100, v189
	v_mov_b32_e32 v101, v189
	v_mov_b32_e32 v102, 0
	v_mov_b32_e32 v103, v189
	v_mov_b32_e32 v104, v189
	v_mov_b32_e32 v105, v189
	v_mov_b32_e32 v114, 0
	v_mov_b32_e32 v115, v189
	v_mov_b32_e32 v116, v189
	v_mov_b32_e32 v117, v189
	v_mov_b32_e32 v122, 0
	v_mov_b32_e32 v123, v189
	v_mov_b32_e32 v124, v189
	v_mov_b32_e32 v125, v189
	v_mov_b32_e32 v126, 0
	v_mov_b32_e32 v127, v189
	v_mov_b32_e32 v128, v189
	v_mov_b32_e32 v129, v189
	v_mov_b32_e32 v130, 0
	v_mov_b32_e32 v131, v189
	v_mov_b32_e32 v132, v189
	v_mov_b32_e32 v133, v189
	v_mov_b32_e32 v134, 0
	v_mov_b32_e32 v135, v189
	v_mov_b32_e32 v136, v189
	v_mov_b32_e32 v137, v189
	s_waitcnt lgkmcnt(0)
	s_lshl_b32 s95, s98, 18
	s_add_u32 s95, s95, 0x1000
	s_add_u32 s30, s95, s94
	s_add_u32 s26, s72, s30
	s_addc_u32 s27, s73, 0
	s_add_u32 s28, s74, s30
	s_addc_u32 s29, s75, 0
	s_add_u32 s94, s94, 0x2000
	s_and_b32 s94, s94, 0x3ffff
	global_load_dwordx4 v[18:21], v184, s[26:27] offset:-4096 nt
	global_load_dwordx4 v[22:25], v184, s[28:29] offset:-4096 nt
	global_load_dwordx4 v[26:29], v184, s[26:27] nt
	global_load_dwordx4 v[34:37], v184, s[28:29] nt
	s_add_u32 s30, s95, s94
	s_add_u32 s26, s72, s30
	s_addc_u32 s27, s73, 0
	s_add_u32 s28, s74, s30
	s_addc_u32 s29, s75, 0
	s_add_u32 s94, s94, 0x2000
	s_and_b32 s94, s94, 0x3ffff
	global_load_dwordx4 v[30:33], v184, s[26:27] offset:-4096 nt
	global_load_dwordx4 v[38:41], v184, s[28:29] offset:-4096 nt
.LBB0_596:
	s_add_i32 s25, s24, 1
	s_cmp_eq_u32 s24, 15
	s_cbranch_scc1 .Lsp_last_b
	s_waitcnt vmcnt(4)
	v_cvt_pk_bf16_f32 v240, v18, v19
	v_cvt_pk_bf16_f32 v241, v20, v21
	ds_write_b64 v190, v[240:241]
	v_cvt_pk_bf16_f32 v180, v22, v23
	v_cvt_pk_bf16_f32 v181, v24, v25
	ds_write_b64 v191, v[180:181] offset:8192
	global_load_dwordx4 v[42:45], v184, s[26:27] nt
	global_load_dwordx4 v[50:53], v184, s[28:29] nt
	s_waitcnt vmcnt(4)
	v_cvt_pk_bf16_f32 v240, v26, v27
	v_cvt_pk_bf16_f32 v241, v28, v29
	ds_write_b64 v192, v[240:241]
	v_cvt_pk_bf16_f32 v180, v34, v35
	v_cvt_pk_bf16_f32 v181, v36, v37
	ds_write_b64 v193, v[180:181] offset:8192
	s_add_u32 s30, s95, s94
	s_add_u32 s26, s72, s30
	s_addc_u32 s27, s73, 0
	s_add_u32 s28, s74, s30
	s_addc_u32 s29, s75, 0
	s_add_u32 s94, s94, 0x2000
	s_and_b32 s94, s94, 0x3ffff
	global_load_dwordx4 v[46:49], v184, s[26:27] offset:-4096 nt
	global_load_dwordx4 v[54:57], v184, s[28:29] offset:-4096 nt
	s_waitcnt vmcnt(4)
	v_cvt_pk_bf16_f32 v240, v30, v31
	v_cvt_pk_bf16_f32 v241, v32, v33
	ds_write_b64 v194, v[240:241]
	v_cvt_pk_bf16_f32 v180, v38, v39
	v_cvt_pk_bf16_f32 v181, v40, v41
	ds_write_b64 v195, v[180:181] offset:8192
	global_load_dwordx4 v[58:61], v184, s[26:27] nt
	global_load_dwordx4 v[66:69], v184, s[28:29] nt
	s_waitcnt vmcnt(4)
	v_cvt_pk_bf16_f32 v240, v42, v43
	v_cvt_pk_bf16_f32 v241, v44, v45
	ds_write_b64 v197, v[240:241]
	v_cvt_pk_bf16_f32 v180, v50, v51
	v_cvt_pk_bf16_f32 v181, v52, v53
	ds_write_b64 v198, v[180:181] offset:8192
	s_add_u32 s30, s95, s94
	s_add_u32 s26, s72, s30
	s_addc_u32 s27, s73, 0
	s_add_u32 s28, s74, s30
	s_addc_u32 s29, s75, 0
	s_add_u32 s94, s94, 0x2000
	s_and_b32 s94, s94, 0x3ffff
	global_load_dwordx4 v[62:65], v184, s[26:27] offset:-4096 nt
	global_load_dwordx4 v[70:73], v184, s[28:29] offset:-4096 nt
	s_waitcnt vmcnt(4)
	v_cvt_pk_bf16_f32 v240, v46, v47
	v_cvt_pk_bf16_f32 v241, v48, v49
	ds_write_b64 v199, v[240:241]
	v_cvt_pk_bf16_f32 v180, v54, v55
	v_cvt_pk_bf16_f32 v181, v56, v57
	ds_write_b64 v200, v[180:181] offset:8192
	global_load_dwordx4 v[74:77], v184, s[26:27] nt
	global_load_dwordx4 v[82:85], v184, s[28:29] nt
	s_waitcnt vmcnt(4)
	v_cvt_pk_bf16_f32 v240, v58, v59
	v_cvt_pk_bf16_f32 v241, v60, v61
	ds_write_b64 v201, v[240:241]
	v_cvt_pk_bf16_f32 v180, v66, v67
	v_cvt_pk_bf16_f32 v181, v68, v69
	ds_write_b64 v202, v[180:181] offset:8192
	s_add_u32 s30, s95, s94
	s_add_u32 s26, s72, s30
	s_addc_u32 s27, s73, 0
	s_add_u32 s28, s74, s30
	s_addc_u32 s29, s75, 0
	s_add_u32 s94, s94, 0x2000
	s_and_b32 s94, s94, 0x3ffff
	global_load_dwordx4 v[78:81], v184, s[26:27] offset:-4096 nt
	global_load_dwordx4 v[86:89], v184, s[28:29] offset:-4096 nt
	s_waitcnt vmcnt(4)
	v_cvt_pk_bf16_f32 v240, v62, v63
	v_cvt_pk_bf16_f32 v241, v64, v65
	ds_write_b64 v203, v[240:241]
	v_cvt_pk_bf16_f32 v180, v70, v71
	v_cvt_pk_bf16_f32 v181, v72, v73
	ds_write_b64 v204, v[180:181] offset:8192
	global_load_dwordx4 v[90:93], v184, s[26:27] nt
	global_load_dwordx4 v[110:113], v184, s[28:29] nt
	s_waitcnt vmcnt(4)
	v_cvt_pk_bf16_f32 v240, v74, v75
	v_cvt_pk_bf16_f32 v241, v76, v77
	ds_write_b64 v205, v[240:241]
	v_cvt_pk_bf16_f32 v180, v82, v83
	v_cvt_pk_bf16_f32 v181, v84, v85
	ds_write_b64 v206, v[180:181] offset:8192
	s_add_u32 s30, s95, s94
	s_add_u32 s26, s72, s30
	s_addc_u32 s27, s73, 0
	s_add_u32 s28, s74, s30
	s_addc_u32 s29, s75, 0
	s_add_u32 s94, s94, 0x2000
	s_and_b32 s94, s94, 0x3ffff
	global_load_dwordx4 v[106:109], v184, s[26:27] offset:-4096 nt
	global_load_dwordx4 v[118:121], v184, s[28:29] offset:-4096 nt
	s_waitcnt vmcnt(4)
	v_cvt_pk_bf16_f32 v240, v78, v79
	v_cvt_pk_bf16_f32 v241, v80, v81
	ds_write_b64 v190, v[240:241] offset:4096
	v_cvt_pk_bf16_f32 v180, v86, v87
	v_cvt_pk_bf16_f32 v181, v88, v89
	ds_write_b64 v191, v[180:181] offset:12288
	global_load_dwordx4 v[138:141], v184, s[26:27] nt
	global_load_dwordx4 v[142:145], v184, s[28:29] nt
	s_waitcnt vmcnt(4)
	v_cvt_pk_bf16_f32 v240, v90, v91
	v_cvt_pk_bf16_f32 v241, v92, v93
	ds_write_b64 v207, v[240:241]
	v_cvt_pk_bf16_f32 v180, v110, v111
	v_cvt_pk_bf16_f32 v181, v112, v113
	ds_write_b64 v208, v[180:181] offset:8192
	s_add_u32 s30, s95, s94
	s_add_u32 s26, s72, s30
	s_addc_u32 s27, s73, 0
	s_add_u32 s28, s74, s30
	s_addc_u32 s29, s75, 0
	s_add_u32 s94, s94, 0x2000
	s_and_b32 s94, s94, 0x3ffff
	global_load_dwordx4 v[146:149], v184, s[26:27] offset:-4096 nt
	global_load_dwordx4 v[150:153], v184, s[28:29] offset:-4096 nt
	s_waitcnt vmcnt(4)
	v_cvt_pk_bf16_f32 v240, v106, v107
	v_cvt_pk_bf16_f32 v241, v108, v109
	ds_write_b64 v209, v[240:241]
	v_cvt_pk_bf16_f32 v180, v118, v119
	v_cvt_pk_bf16_f32 v181, v120, v121
	ds_write_b64 v210, v[180:181] offset:8192
	global_load_dwordx4 v[154:157], v184, s[26:27] nt
	global_load_dwordx4 v[158:161], v184, s[28:29] nt
	s_waitcnt vmcnt(4)
	v_cvt_pk_bf16_f32 v240, v138, v139
	v_cvt_pk_bf16_f32 v241, v140, v141
	ds_write_b64 v211, v[240:241]
	v_cvt_pk_bf16_f32 v180, v142, v143
	v_cvt_pk_bf16_f32 v181, v144, v145
	ds_write_b64 v212, v[180:181] offset:8192
	s_add_u32 s30, s95, s94
	s_add_u32 s26, s72, s30
	s_addc_u32 s27, s73, 0
	s_add_u32 s28, s74, s30
	s_addc_u32 s29, s75, 0
	s_add_u32 s94, s94, 0x2000
	s_and_b32 s94, s94, 0x3ffff
	global_load_dwordx4 v[162:165], v184, s[26:27] offset:-4096 nt
	global_load_dwordx4 v[166:169], v184, s[28:29] offset:-4096 nt
	s_waitcnt vmcnt(4)
	v_cvt_pk_bf16_f32 v240, v146, v147
	v_cvt_pk_bf16_f32 v241, v148, v149
	ds_write_b64 v213, v[240:241]
	v_cvt_pk_bf16_f32 v180, v150, v151
	v_cvt_pk_bf16_f32 v181, v152, v153
	ds_write_b64 v214, v[180:181] offset:8192
	global_load_dwordx4 v[170:173], v184, s[26:27] nt
	global_load_dwordx4 v[174:177], v184, s[28:29] nt
	s_lshr_b32 s30, s25, 2
	s_cmp_lt_u32 s30, 2
	s_cselect_b32 s95, s98, s100
	s_cselect_b32 s97, s99, s101
	s_bitcmp1_b32 s30, 0
	s_cselect_b32 s95, s97, s95
	s_lshl_b32 s95, s95, 18
	s_add_u32 s95, s95, 0x1000
	s_waitcnt vmcnt(4)
	v_cvt_pk_bf16_f32 v240, v154, v155
	v_cvt_pk_bf16_f32 v241, v156, v157
	ds_write_b64 v215, v[240:241]
	v_cvt_pk_bf16_f32 v180, v158, v159
	v_cvt_pk_bf16_f32 v181, v160, v161
	ds_write_b64 v216, v[180:181] offset:8192
	s_add_u32 s30, s95, s94
	s_add_u32 s26, s72, s30
	s_addc_u32 s27, s73, 0
	s_add_u32 s28, s74, s30
	s_addc_u32 s29, s75, 0
	s_add_u32 s94, s94, 0x2000
	s_and_b32 s94, s94, 0x3ffff
	global_load_dwordx4 v[18:21], v184, s[26:27] offset:-4096 nt
	global_load_dwordx4 v[22:25], v184, s[28:29] offset:-4096 nt
	s_waitcnt vmcnt(4)
	v_cvt_pk_bf16_f32 v240, v162, v163
	v_cvt_pk_bf16_f32 v241, v164, v165
	ds_write_b64 v217, v[240:241]
	v_cvt_pk_bf16_f32 v180, v166, v167
	v_cvt_pk_bf16_f32 v181, v168, v169
	ds_write_b64 v218, v[180:181] offset:8192
	global_load_dwordx4 v[26:29], v184, s[26:27] nt
	global_load_dwordx4 v[34:37], v184, s[28:29] nt
	s_waitcnt vmcnt(4)
	v_cvt_pk_bf16_f32 v240, v170, v171
	v_cvt_pk_bf16_f32 v241, v172, v173
	ds_write_b64 v219, v[240:241]
	v_cvt_pk_bf16_f32 v180, v174, v175
	v_cvt_pk_bf16_f32 v181, v176, v177
	ds_write_b64 v220, v[180:181] offset:8192
	s_add_u32 s30, s95, s94
	s_add_u32 s26, s72, s30
	s_addc_u32 s27, s73, 0
	s_add_u32 s28, s74, s30
	s_addc_u32 s29, s75, 0
	s_add_u32 s94, s94, 0x2000
	s_and_b32 s94, s94, 0x3ffff
	global_load_dwordx4 v[30:33], v184, s[26:27] offset:-4096 nt
	global_load_dwordx4 v[38:41], v184, s[28:29] offset:-4096 nt
	s_branch .LBB0_600
.Lsp_last_b:
	s_waitcnt vmcnt(4)
	v_cvt_pk_bf16_f32 v240, v18, v19
	v_cvt_pk_bf16_f32 v241, v20, v21
	ds_write_b64 v190, v[240:241]
	v_cvt_pk_bf16_f32 v180, v22, v23
	v_cvt_pk_bf16_f32 v181, v24, v25
	ds_write_b64 v191, v[180:181] offset:8192
	global_load_dwordx4 v[42:45], v184, s[26:27] nt
	global_load_dwordx4 v[50:53], v184, s[28:29] nt
	s_waitcnt vmcnt(4)
	v_cvt_pk_bf16_f32 v240, v26, v27
	v_cvt_pk_bf16_f32 v241, v28, v29
	ds_write_b64 v192, v[240:241]
	v_cvt_pk_bf16_f32 v180, v34, v35
	v_cvt_pk_bf16_f32 v181, v36, v37
	ds_write_b64 v193, v[180:181] offset:8192
	s_add_u32 s30, s95, s94
	s_add_u32 s26, s72, s30
	s_addc_u32 s27, s73, 0
	s_add_u32 s28, s74, s30
	s_addc_u32 s29, s75, 0
	s_add_u32 s94, s94, 0x2000
	s_and_b32 s94, s94, 0x3ffff
	global_load_dwordx4 v[46:49], v184, s[26:27] offset:-4096 nt
	global_load_dwordx4 v[54:57], v184, s[28:29] offset:-4096 nt
	s_waitcnt vmcnt(4)
	v_cvt_pk_bf16_f32 v240, v30, v31
	v_cvt_pk_bf16_f32 v241, v32, v33
	ds_write_b64 v194, v[240:241]
	v_cvt_pk_bf16_f32 v180, v38, v39
	v_cvt_pk_bf16_f32 v181, v40, v41
	ds_write_b64 v195, v[180:181] offset:8192
	global_load_dwordx4 v[58:61], v184, s[26:27] nt
	global_load_dwordx4 v[66:69], v184, s[28:29] nt
	s_waitcnt vmcnt(4)
	v_cvt_pk_bf16_f32 v240, v42, v43
	v_cvt_pk_bf16_f32 v241, v44, v45
	ds_write_b64 v197, v[240:241]
	v_cvt_pk_bf16_f32 v180, v50, v51
	v_cvt_pk_bf16_f32 v181, v52, v53
	ds_write_b64 v198, v[180:181] offset:8192
	s_add_u32 s30, s95, s94
	s_add_u32 s26, s72, s30
	s_addc_u32 s27, s73, 0
	s_add_u32 s28, s74, s30
	s_addc_u32 s29, s75, 0
	s_add_u32 s94, s94, 0x2000
	s_and_b32 s94, s94, 0x3ffff
	global_load_dwordx4 v[62:65], v184, s[26:27] offset:-4096 nt
	global_load_dwordx4 v[70:73], v184, s[28:29] offset:-4096 nt
	s_waitcnt vmcnt(4)
	v_cvt_pk_bf16_f32 v240, v46, v47
	v_cvt_pk_bf16_f32 v241, v48, v49
	ds_write_b64 v199, v[240:241]
	v_cvt_pk_bf16_f32 v180, v54, v55
	v_cvt_pk_bf16_f32 v181, v56, v57
	ds_write_b64 v200, v[180:181] offset:8192
	global_load_dwordx4 v[74:77], v184, s[26:27] nt
	global_load_dwordx4 v[82:85], v184, s[28:29] nt
	s_waitcnt vmcnt(4)
	v_cvt_pk_bf16_f32 v240, v58, v59
	v_cvt_pk_bf16_f32 v241, v60, v61
	ds_write_b64 v201, v[240:241]
	v_cvt_pk_bf16_f32 v180, v66, v67
	v_cvt_pk_bf16_f32 v181, v68, v69
	ds_write_b64 v202, v[180:181] offset:8192
	s_add_u32 s30, s95, s94
	s_add_u32 s26, s72, s30
	s_addc_u32 s27, s73, 0
	s_add_u32 s28, s74, s30
	s_addc_u32 s29, s75, 0
	s_add_u32 s94, s94, 0x2000
	s_and_b32 s94, s94, 0x3ffff
	global_load_dwordx4 v[78:81], v184, s[26:27] offset:-4096 nt
	global_load_dwordx4 v[86:89], v184, s[28:29] offset:-4096 nt
	s_waitcnt vmcnt(4)
	v_cvt_pk_bf16_f32 v240, v62, v63
	v_cvt_pk_bf16_f32 v241, v64, v65
	ds_write_b64 v203, v[240:241]
	v_cvt_pk_bf16_f32 v180, v70, v71
	v_cvt_pk_bf16_f32 v181, v72, v73
	ds_write_b64 v204, v[180:181] offset:8192
	global_load_dwordx4 v[90:93], v184, s[26:27] nt
	global_load_dwordx4 v[110:113], v184, s[28:29] nt
	s_waitcnt vmcnt(4)
	v_cvt_pk_bf16_f32 v240, v74, v75
	v_cvt_pk_bf16_f32 v241, v76, v77
	ds_write_b64 v205, v[240:241]
	v_cvt_pk_bf16_f32 v180, v82, v83
	v_cvt_pk_bf16_f32 v181, v84, v85
	ds_write_b64 v206, v[180:181] offset:8192
	s_add_u32 s30, s95, s94
	s_add_u32 s26, s72, s30
	s_addc_u32 s27, s73, 0
	s_add_u32 s28, s74, s30
	s_addc_u32 s29, s75, 0
	s_add_u32 s94, s94, 0x2000
	s_and_b32 s94, s94, 0x3ffff
	global_load_dwordx4 v[106:109], v184, s[26:27] offset:-4096 nt
	global_load_dwordx4 v[118:121], v184, s[28:29] offset:-4096 nt
	s_waitcnt vmcnt(4)
	v_cvt_pk_bf16_f32 v240, v78, v79
	v_cvt_pk_bf16_f32 v241, v80, v81
	ds_write_b64 v190, v[240:241] offset:4096
	v_cvt_pk_bf16_f32 v180, v86, v87
	v_cvt_pk_bf16_f32 v181, v88, v89
	ds_write_b64 v191, v[180:181] offset:12288
	global_load_dwordx4 v[138:141], v184, s[26:27] nt
	global_load_dwordx4 v[142:145], v184, s[28:29] nt
	s_waitcnt vmcnt(4)
	v_cvt_pk_bf16_f32 v240, v90, v91
	v_cvt_pk_bf16_f32 v241, v92, v93
	ds_write_b64 v207, v[240:241]
	v_cvt_pk_bf16_f32 v180, v110, v111
	v_cvt_pk_bf16_f32 v181, v112, v113
	ds_write_b64 v208, v[180:181] offset:8192
	s_add_u32 s30, s95, s94
	s_add_u32 s26, s72, s30
	s_addc_u32 s27, s73, 0
	s_add_u32 s28, s74, s30
	s_addc_u32 s29, s75, 0
	s_add_u32 s94, s94, 0x2000
	s_and_b32 s94, s94, 0x3ffff
	global_load_dwordx4 v[146:149], v184, s[26:27] offset:-4096 nt
	global_load_dwordx4 v[150:153], v184, s[28:29] offset:-4096 nt
	s_waitcnt vmcnt(4)
	v_cvt_pk_bf16_f32 v240, v106, v107
	v_cvt_pk_bf16_f32 v241, v108, v109
	ds_write_b64 v209, v[240:241]
	v_cvt_pk_bf16_f32 v180, v118, v119
	v_cvt_pk_bf16_f32 v181, v120, v121
	ds_write_b64 v210, v[180:181] offset:8192
	global_load_dwordx4 v[154:157], v184, s[26:27] nt
	global_load_dwordx4 v[158:161], v184, s[28:29] nt
	s_waitcnt vmcnt(4)
	v_cvt_pk_bf16_f32 v240, v138, v139
	v_cvt_pk_bf16_f32 v241, v140, v141
	ds_write_b64 v211, v[240:241]
	v_cvt_pk_bf16_f32 v180, v142, v143
	v_cvt_pk_bf16_f32 v181, v144, v145
	ds_write_b64 v212, v[180:181] offset:8192
	s_add_u32 s30, s95, s94
	s_add_u32 s26, s72, s30
	s_addc_u32 s27, s73, 0
	s_add_u32 s28, s74, s30
	s_addc_u32 s29, s75, 0
	s_add_u32 s94, s94, 0x2000
	s_and_b32 s94, s94, 0x3ffff
	global_load_dwordx4 v[162:165], v184, s[26:27] offset:-4096 nt
	global_load_dwordx4 v[166:169], v184, s[28:29] offset:-4096 nt
	s_waitcnt vmcnt(4)
	v_cvt_pk_bf16_f32 v240, v146, v147
	v_cvt_pk_bf16_f32 v241, v148, v149
	ds_write_b64 v213, v[240:241]
	v_cvt_pk_bf16_f32 v180, v150, v151
	v_cvt_pk_bf16_f32 v181, v152, v153
	ds_write_b64 v214, v[180:181] offset:8192
	global_load_dwordx4 v[170:173], v184, s[26:27] nt
	global_load_dwordx4 v[174:177], v184, s[28:29] nt
	s_waitcnt vmcnt(4)
	v_cvt_pk_bf16_f32 v240, v154, v155
	v_cvt_pk_bf16_f32 v241, v156, v157
	ds_write_b64 v215, v[240:241]
	v_cvt_pk_bf16_f32 v180, v158, v159
	v_cvt_pk_bf16_f32 v181, v160, v161
	ds_write_b64 v216, v[180:181] offset:8192
	s_waitcnt vmcnt(2)
	v_cvt_pk_bf16_f32 v240, v162, v163
	v_cvt_pk_bf16_f32 v241, v164, v165
	ds_write_b64 v217, v[240:241]
	v_cvt_pk_bf16_f32 v180, v166, v167
	v_cvt_pk_bf16_f32 v181, v168, v169
	ds_write_b64 v218, v[180:181] offset:8192
	s_waitcnt vmcnt(0)
	v_cvt_pk_bf16_f32 v240, v170, v171
	v_cvt_pk_bf16_f32 v241, v172, v173
	ds_write_b64 v219, v[240:241]
	v_cvt_pk_bf16_f32 v180, v174, v175
	v_cvt_pk_bf16_f32 v181, v176, v177
	ds_write_b64 v220, v[180:181] offset:8192
	s_branch .LBB0_600
